# adds: NA second-half bias reads use an immediate offset from the first half's base (no index select/address VALU); prep0 q|k|v pieces loaded together
# speedup vs baseline: 1.0134x; 1.0134x over previous
; __device__ __forceinline__ float red8(float x) { x += dppf<0xB1>(x); x += dppf<0x4E>(x); x += dppf<0x141>(x); return x; }
; __device__ __forceinline__ u32x4 pack8(const float (&x)[8]) { u32x4 o; o.x = pk2(x[0], x[1]); o.y = pk2(x[2], x[3]); o.z = pk2(x[4], x[5]); o.w = pk2(x[6], x[7]); return o; }
; __device__ __forceinline__ void phase_prep0() {
;     ...
;         for (int p = 0; p < 3; ++p) {
;             const u32x4 raw = *(const u32x4*)(prow + p * 512 + lane * 8); float x[8]; unpack8(raw, x);
;             float ss = 0.f;
; #pragma unroll
;             for (int e = 0; e < 8; ++e) ss += x[e] * x[e];
;             ss = red8(ss); const float rs = rsqrtf(ss * (1.f / 64.f) + 1e-6f);
;             float y[8];
; #pragma unroll
;             for (int e = 0; e < 8; ++e) y[e] = x[e] * rs * (p < 2 ? qn[e] : kn[e]);
;             if (!isc) {
; #pragma unroll
;                 for (int e = 0; e < 8; ++e) { const float o = __shfl_xor(y[e], 4); y[e] = (l7 < 4) ? y[e] * cs[e] - o * sn[e] : y[e] * cs[e] + o * sn[e]; } }
;             if (p < 2) {
; #pragma unroll
;                 for (int e = 0; e < 8; ++e) y[e] *= 0.125f * LOG2E;
;                 *(u32x4*)(Q0 + (size_t)row * 1024 + p * 512 + lane * 8) = pack8(y);
.LBB0_350:
	s_or_b64 exec, exec, s[14:15]
	s_add_u32 s98, s98, s99
	v_lshl_add_u64 v[122:123], v[120:121], 0, v[66:67]
	v_add_co_u32_e32 v222, vcc, 0x11000000, v122
	s_nop 1
	v_addc_co_u32_e32 v223, vcc, 0, v123, vcc
	global_load_dwordx4 v[224:227], v[222:223], off
	global_load_dwordx4 v[228:231], v[222:223], off offset:1024
	global_load_dwordx4 v[232:235], v[222:223], off offset:2048
	s_waitcnt vmcnt(0)
	v_mov_b32_e32 v80, v224
	v_mov_b32_e32 v81, v225
	v_mov_b32_e32 v82, v226
	v_mov_b32_e32 v83, v227
	v_lshlrev_b32_e32 v124, 16, v80
	v_and_b32_e32 v125, 0xffff0000, v80
	v_lshlrev_b32_e32 v80, 16, v81
	v_and_b32_e32 v81, 0xffff0000, v81
	v_pk_mul_f32 v[128:129], v[124:125], v[124:125]
	v_pk_mul_f32 v[130:131], v[80:81], v[80:81]
	v_add_f32_e32 v104, v128, v129
	v_lshlrev_b32_e32 v126, 16, v82
	v_and_b32_e32 v127, 0xffff0000, v82
	v_add_f32_e32 v104, v130, v104
	v_pk_mul_f32 v[132:133], v[126:127], v[126:127]
	v_add_f32_e32 v104, v131, v104
	v_lshlrev_b32_e32 v82, 16, v83
	v_and_b32_e32 v83, 0xffff0000, v83
	v_add_f32_e32 v104, v132, v104
	v_pk_mul_f32 v[134:135], v[82:83], v[82:83]
	v_add_f32_e32 v104, v133, v104
	v_add_f32_e32 v104, v134, v104
	v_add_f32_e32 v104, v135, v104
	s_nop 1
	v_add_f32_dpp v104, v104, v104 quad_perm:[1,0,3,2] row_mask:0xf bank_mask:0xf bound_ctrl:1
	s_nop 1
	v_add_f32_dpp v104, v104, v104 quad_perm:[2,3,0,1] row_mask:0xf bank_mask:0xf bound_ctrl:1
	s_nop 1
	v_add_f32_dpp v104, v104, v104 row_half_mirror row_mask:0xf bank_mask:0xf bound_ctrl:1
	v_fmamk_f32 v104, v104, 0x3c800000, v154
	v_mul_f32_e32 v128, 0x4b800000, v104
	v_cmp_gt_f32_e32 vcc, s1, v104
	s_nop 1
	v_cndmask_b32_e32 v104, v104, v128, vcc
	v_rsq_f32_e32 v128, v104
	v_mbcnt_hi_u32_b32 v104, -1, v220
	v_mul_f32_e32 v129, 0x45800000, v128
	v_cndmask_b32_e32 v128, v128, v129, vcc
	v_pk_mul_f32 v[124:125], v[128:129], v[124:125] op_sel_hi:[0,1]
	v_pk_mul_f32 v[130:131], v[128:129], v[80:81] op_sel_hi:[0,1]
	v_pk_mul_f32 v[126:127], v[128:129], v[126:127] op_sel_hi:[0,1]
	v_pk_mul_f32 v[128:129], v[128:129], v[82:83] op_sel_hi:[0,1]
	v_pk_mul_f32 v[80:81], v[52:53], v[124:125]
	v_pk_mul_f32 v[82:83], v[54:55], v[130:131]
	v_pk_mul_f32 v[124:125], v[48:49], v[126:127]
	v_pk_mul_f32 v[126:127], v[50:51], v[128:129]
	v_mov_b32_e32 v130, v80
	v_mov_b32_e32 v132, v81
	v_mov_b32_e32 v131, v82
	v_mov_b32_e32 v133, v83
	v_mov_b32_e32 v128, v124
	v_mov_b32_e32 v134, v125
	v_mov_b32_e32 v129, v126
	v_mov_b32_e32 v135, v127
	s_and_saveexec_b64 s[8:9], s[50:51]
	s_cbranch_execz .LBB0_352
	v_and_b32_e32 v129, 64, v104
	v_xor_b32_e32 v128, 4, v104
	v_add_u32_e32 v129, 64, v129
	v_cmp_lt_i32_e32 vcc, v128, v129
	s_nop 1
	v_cndmask_b32_e32 v128, v104, v128, vcc
	v_lshlrev_b32_e32 v135, 2, v128
	ds_bpermute_b32 v128, v135, v80
	ds_bpermute_b32 v129, v135, v81
	ds_bpermute_b32 v130, v135, v82
	ds_bpermute_b32 v131, v135, v83
	ds_bpermute_b32 v132, v135, v124
	ds_bpermute_b32 v133, v135, v125
	ds_bpermute_b32 v134, v135, v126
	ds_bpermute_b32 v135, v135, v127
	s_waitcnt lgkmcnt(6)
	v_pk_mul_f32 v[128:129], v[98:99], v[128:129]
	s_waitcnt lgkmcnt(4)
	v_pk_mul_f32 v[130:131], v[94:95], v[130:131]
	s_waitcnt lgkmcnt(2)
	v_pk_mul_f32 v[132:133], v[90:91], v[132:133]
	v_cndmask_b32_e64 v165, v129, -v129, s[38:39]
	s_waitcnt lgkmcnt(0)
	v_pk_mul_f32 v[134:135], v[86:87], v[134:135]
	v_cndmask_b32_e64 v164, v128, -v128, s[38:39]
	v_cndmask_b32_e64 v131, v131, -v131, s[38:39]
	v_cndmask_b32_e64 v130, v130, -v130, s[38:39]
	v_cndmask_b32_e64 v129, v133, -v133, s[38:39]
	v_cndmask_b32_e64 v128, v132, -v132, s[38:39]
	v_cndmask_b32_e64 v133, v135, -v135, s[38:39]
	v_cndmask_b32_e64 v132, v134, -v134, s[38:39]
	v_pk_fma_f32 v[126:127], v[84:85], v[126:127], v[132:133]
	v_pk_fma_f32 v[128:129], v[88:89], v[124:125], v[128:129]
	v_pk_fma_f32 v[82:83], v[92:93], v[82:83], v[130:131]
	v_pk_fma_f32 v[130:131], v[96:97], v[80:81], v[164:165]
	v_mov_b32_e32 v133, v83
	v_mov_b32_e32 v132, v131
	v_mov_b32_e32 v131, v82
	v_mov_b32_e32 v134, v129
	v_mov_b32_e32 v129, v126
	v_mov_b32_e32 v135, v127
.LBB0_352:
	s_or_b64 exec, exec, s[8:9]
	v_pk_mul_f32 v[124:125], v[132:133], s[70:71] op_sel_hi:[1,0]
	v_pk_mul_f32 v[126:127], v[128:129], s[70:71] op_sel_hi:[1,0]
	v_pk_mul_f32 v[128:129], v[134:135], s[70:71] op_sel_hi:[1,0]
	v_pk_mul_f32 v[82:83], v[130:131], s[70:71] op_sel_hi:[1,0]
	v_bfe_u32 v130, v129, 16, 1
	v_bfe_u32 v131, v128, 16, 1
	v_bfe_u32 v132, v125, 16, 1
	v_bfe_u32 v133, v124, 16, 1
	v_lshl_add_u64 v[80:81], v[118:119], 0, v[66:67]
	v_add3_u32 v124, v124, v133, s31
	v_add3_u32 v125, v125, v132, s31
	v_add3_u32 v128, v128, v131, s31
	v_add3_u32 v129, v129, v130, s31
	v_bfe_u32 v130, v82, 16, 1
	v_bfe_u32 v131, v83, 16, 1
	v_bfe_u32 v132, v126, 16, 1
	v_bfe_u32 v133, v127, 16, 1
	s_mov_b32 s8, 0x4400000
	v_add3_u32 v127, v127, v133, s31
	v_add3_u32 v126, v126, v132, s31
	v_add3_u32 v83, v83, v131, s31
	v_add3_u32 v82, v82, v130, s31
	v_add_co_u32_e32 v80, vcc, s8, v80
	v_lshrrev_b32_e32 v82, 16, v82
	v_lshrrev_b32_e32 v83, 16, v83
	v_lshrrev_b32_e32 v126, 16, v126
	v_lshrrev_b32_e32 v127, 16, v127
	v_addc_co_u32_e32 v81, vcc, 0, v81, vcc
	s_mov_b32 s8, 0x11000000
	v_and_or_b32 v127, v129, s30, v127
	v_and_or_b32 v126, v128, s30, v126
	v_and_or_b32 v125, v125, s30, v83
	v_and_or_b32 v124, v124, s30, v82
	v_add_co_u32_e32 v82, vcc, s8, v122
	global_store_dwordx4 v[80:81], v[124:127], off
	s_nop 0
	v_addc_co_u32_e32 v83, vcc, 0, v123, vcc
	v_mov_b32_e32 v124, v228
	v_mov_b32_e32 v125, v229
	v_mov_b32_e32 v126, v230
	v_mov_b32_e32 v127, v231
	v_lshlrev_b32_e32 v128, 16, v124
	v_and_b32_e32 v129, 0xffff0000, v124
	v_lshlrev_b32_e32 v124, 16, v125
	v_and_b32_e32 v125, 0xffff0000, v125
; __device__ __forceinline__ float red8(float x) { x += dppf<0xB1>(x); x += dppf<0x4E>(x); x += dppf<0x141>(x); return x; }
; __device__ __forceinline__ u32x4 pack8(const float (&x)[8]) { u32x4 o; o.x = pk2(x[0], x[1]); o.y = pk2(x[2], x[3]); o.z = pk2(x[4], x[5]); o.w = pk2(x[6], x[7]); return o; }
; __device__ __forceinline__ void phase_prep0() {
;     ...
;             const u32x4 raw = *(const u32x4*)(prow + p * 512 + lane * 8); float x[8]; unpack8(raw, x);
;             float ss = 0.f;
; #pragma unroll
;             for (int e = 0; e < 8; ++e) ss += x[e] * x[e];
;             ss = red8(ss); const float rs = rsqrtf(ss * (1.f / 64.f) + 1e-6f);
;             float y[8];
; #pragma unroll
;             for (int e = 0; e < 8; ++e) y[e] = x[e] * rs * (p < 2 ? qn[e] : kn[e]);
;             if (!isc) {
; #pragma unroll
;                 for (int e = 0; e < 8; ++e) { const float o = __shfl_xor(y[e], 4); y[e] = (l7 < 4) ? y[e] * cs[e] - o * sn[e] : y[e] * cs[e] + o * sn[e]; } }
;             if (p < 2) {
; #pragma unroll
;                 for (int e = 0; e < 8; ++e) y[e] *= 0.125f * LOG2E;
;                 *(u32x4*)(Q0 + (size_t)row * 1024 + p * 512 + lane * 8) = pack8(y);
	v_pk_mul_f32 v[132:133], v[128:129], v[128:129]
	v_pk_mul_f32 v[134:135], v[124:125], v[124:125]
	v_add_f32_e32 v132, v132, v133
	v_lshlrev_b32_e32 v130, 16, v126
	v_and_b32_e32 v131, 0xffff0000, v126
	v_add_f32_e32 v132, v134, v132
	v_pk_mul_f32 v[164:165], v[130:131], v[130:131]
	v_add_f32_e32 v132, v135, v132
	v_lshlrev_b32_e32 v126, 16, v127
	v_and_b32_e32 v127, 0xffff0000, v127
	v_add_f32_e32 v132, v164, v132
	v_pk_mul_f32 v[166:167], v[126:127], v[126:127]
	v_add_f32_e32 v132, v165, v132
	v_add_f32_e32 v132, v166, v132
	v_add_f32_e32 v132, v167, v132
	s_nop 1
	v_add_f32_dpp v132, v132, v132 quad_perm:[1,0,3,2] row_mask:0xf bank_mask:0xf bound_ctrl:1
	s_nop 1
	v_add_f32_dpp v132, v132, v132 quad_perm:[2,3,0,1] row_mask:0xf bank_mask:0xf bound_ctrl:1
	s_nop 1
	v_add_f32_dpp v132, v132, v132 row_half_mirror row_mask:0xf bank_mask:0xf bound_ctrl:1
	v_fmamk_f32 v132, v132, 0x3c800000, v154
	v_mul_f32_e32 v133, 0x4b800000, v132
	v_cmp_gt_f32_e32 vcc, s1, v132
	s_nop 1
	v_cndmask_b32_e32 v132, v132, v133, vcc
	v_rsq_f32_e32 v132, v132
	s_nop 0
	v_mul_f32_e32 v133, 0x45800000, v132
	v_cndmask_b32_e32 v132, v132, v133, vcc
	v_pk_mul_f32 v[128:129], v[132:133], v[128:129] op_sel_hi:[0,1]
	v_pk_mul_f32 v[124:125], v[132:133], v[124:125] op_sel_hi:[0,1]
	v_pk_mul_f32 v[134:135], v[132:133], v[130:131] op_sel_hi:[0,1]
	v_pk_mul_f32 v[132:133], v[132:133], v[126:127] op_sel_hi:[0,1]
	v_pk_mul_f32 v[130:131], v[52:53], v[128:129]
	v_pk_mul_f32 v[128:129], v[54:55], v[124:125]
	v_pk_mul_f32 v[126:127], v[48:49], v[134:135]
	v_pk_mul_f32 v[124:125], v[50:51], v[132:133]
	s_and_saveexec_b64 s[8:9], s[50:51]
	s_cbranch_execz .LBB0_354
	v_and_b32_e32 v133, 64, v104
	v_xor_b32_e32 v132, 4, v104
	v_add_u32_e32 v133, 64, v133
	v_cmp_lt_i32_e32 vcc, v132, v133
	s_nop 1
	v_cndmask_b32_e32 v132, v104, v132, vcc
	v_lshlrev_b32_e32 v167, 2, v132
	ds_bpermute_b32 v132, v167, v130
	ds_bpermute_b32 v133, v167, v131
	ds_bpermute_b32 v134, v167, v128
	ds_bpermute_b32 v135, v167, v129
	ds_bpermute_b32 v164, v167, v126
	ds_bpermute_b32 v165, v167, v127
	ds_bpermute_b32 v166, v167, v124
	ds_bpermute_b32 v167, v167, v125
	s_waitcnt lgkmcnt(6)
	v_pk_mul_f32 v[132:133], v[98:99], v[132:133]
	s_waitcnt lgkmcnt(4)
	v_pk_mul_f32 v[134:135], v[94:95], v[134:135]
	s_waitcnt lgkmcnt(2)
	v_pk_mul_f32 v[164:165], v[90:91], v[164:165]
	v_cndmask_b32_e64 v133, v133, -v133, s[38:39]
	s_waitcnt lgkmcnt(0)
	v_pk_mul_f32 v[166:167], v[86:87], v[166:167]
	v_cndmask_b32_e64 v132, v132, -v132, s[38:39]
	v_cndmask_b32_e64 v135, v135, -v135, s[38:39]
	v_cndmask_b32_e64 v134, v134, -v134, s[38:39]
	v_cndmask_b32_e64 v165, v165, -v165, s[38:39]
	v_cndmask_b32_e64 v164, v164, -v164, s[38:39]
	v_cndmask_b32_e64 v167, v167, -v167, s[38:39]
	v_cndmask_b32_e64 v166, v166, -v166, s[38:39]
	v_pk_fma_f32 v[124:125], v[84:85], v[124:125], v[166:167]
	v_pk_fma_f32 v[126:127], v[88:89], v[126:127], v[164:165]
	v_pk_fma_f32 v[128:129], v[92:93], v[128:129], v[134:135]
	v_pk_fma_f32 v[130:131], v[96:97], v[130:131], v[132:133]
; __device__ __forceinline__ float red8(float x) { x += dppf<0xB1>(x); x += dppf<0x4E>(x); x += dppf<0x141>(x); return x; }
; __device__ __forceinline__ u32x4 pack8(const float (&x)[8]) { u32x4 o; o.x = pk2(x[0], x[1]); o.y = pk2(x[2], x[3]); o.z = pk2(x[4], x[5]); o.w = pk2(x[6], x[7]); return o; }
; __device__ __forceinline__ void phase_prep0() {
;     ...
;             const u32x4 raw = *(const u32x4*)(prow + p * 512 + lane * 8); float x[8]; unpack8(raw, x);
;             float ss = 0.f;
; #pragma unroll
;             for (int e = 0; e < 8; ++e) ss += x[e] * x[e];
;             ss = red8(ss); const float rs = rsqrtf(ss * (1.f / 64.f) + 1e-6f);
;             float y[8];
; #pragma unroll
;             for (int e = 0; e < 8; ++e) y[e] = x[e] * rs * (p < 2 ? qn[e] : kn[e]);
;             if (!isc) {
; #pragma unroll
;                 for (int e = 0; e < 8; ++e) { const float o = __shfl_xor(y[e], 4); y[e] = (l7 < 4) ? y[e] * cs[e] - o * sn[e] : y[e] * cs[e] + o * sn[e]; } }
;             if (p < 2) {
; #pragma unroll
;                 for (int e = 0; e < 8; ++e) y[e] *= 0.125f * LOG2E;
;                 *(u32x4*)(Q0 + (size_t)row * 1024 + p * 512 + lane * 8) = pack8(y);
;             } else {
;                 const size_t kvo = ((size_t)(b * 4 + ((lane >> 3) & 3)) * KVLEN + kvpos) * 64 + l7 * 8;
;                 if (lane < 32) *(u32x4*)(KALL + kvo) = pack8(y);
;                 else *(u32x4*)(VALL + kvo) = raw;
.LBB0_354:
	s_or_b64 exec, exec, s[8:9]
	v_mov_b32_e32 v133, v128
	v_mov_b32_e32 v128, v131
	v_mov_b32_e32 v131, v124
	v_mov_b32_e32 v124, v127
	v_mov_b32_e32 v132, v130
	v_pk_mul_f32 v[128:129], v[128:129], s[70:71] op_sel_hi:[1,0]
	v_mov_b32_e32 v130, v126
	v_pk_mul_f32 v[124:125], v[124:125], s[70:71] op_sel_hi:[1,0]
	v_pk_mul_f32 v[132:133], v[132:133], s[70:71] op_sel_hi:[1,0]
	v_pk_mul_f32 v[130:131], v[130:131], s[70:71] op_sel_hi:[1,0]
	v_bfe_u32 v126, v125, 16, 1
	v_bfe_u32 v127, v124, 16, 1
	v_bfe_u32 v134, v129, 16, 1
	v_bfe_u32 v135, v128, 16, 1
	v_add3_u32 v128, v128, v135, s31
	v_add3_u32 v129, v129, v134, s31
	v_add3_u32 v124, v124, v127, s31
	v_add3_u32 v125, v125, v126, s31
	v_bfe_u32 v126, v132, 16, 1
	v_bfe_u32 v127, v133, 16, 1
	v_bfe_u32 v134, v130, 16, 1
	v_bfe_u32 v135, v131, 16, 1
	v_add3_u32 v131, v131, v135, s31
	v_add3_u32 v130, v130, v134, s31
	v_add3_u32 v127, v133, v127, s31
	v_add3_u32 v126, v132, v126, s31
	v_lshrrev_b32_e32 v132, 16, v126
	v_lshrrev_b32_e32 v133, 16, v127
	v_lshrrev_b32_e32 v126, 16, v130
	v_lshrrev_b32_e32 v127, 16, v131
	v_and_or_b32 v127, v125, s30, v127
	v_and_or_b32 v126, v124, s30, v126
	v_and_or_b32 v125, v129, s30, v133
	v_and_or_b32 v124, v128, s30, v132
	global_store_dwordx4 v[80:81], v[124:127], off offset:1024
	v_mov_b32_e32 v80, v232
	v_mov_b32_e32 v81, v233
	v_mov_b32_e32 v82, v234
	v_mov_b32_e32 v83, v235
	v_lshlrev_b32_e32 v128, 16, v82
	v_lshlrev_b32_e32 v124, 16, v80
	v_and_b32_e32 v125, 0xffff0000, v80
	v_lshlrev_b32_e32 v126, 16, v81
	v_and_b32_e32 v127, 0xffff0000, v81
	v_pk_mul_f32 v[132:133], v[124:125], v[124:125]
	v_pk_mul_f32 v[134:135], v[126:127], v[126:127]
	v_add_f32_e32 v132, v132, v133
	v_and_b32_e32 v129, 0xffff0000, v82
	v_add_f32_e32 v132, v134, v132
	v_pk_mul_f32 v[164:165], v[128:129], v[128:129]
	v_add_f32_e32 v132, v135, v132
	v_lshlrev_b32_e32 v130, 16, v83
	v_and_b32_e32 v131, 0xffff0000, v83
	v_add_f32_e32 v132, v164, v132
	v_pk_mul_f32 v[166:167], v[130:131], v[130:131]
	v_add_f32_e32 v132, v165, v132
	v_add_f32_e32 v132, v166, v132
	v_add_f32_e32 v132, v167, v132
	s_nop 1
	v_add_f32_dpp v132, v132, v132 quad_perm:[1,0,3,2] row_mask:0xf bank_mask:0xf bound_ctrl:1
	s_nop 1
	v_add_f32_dpp v132, v132, v132 quad_perm:[2,3,0,1] row_mask:0xf bank_mask:0xf bound_ctrl:1
	s_nop 1
	v_add_f32_dpp v132, v132, v132 row_half_mirror row_mask:0xf bank_mask:0xf bound_ctrl:1
	v_fmamk_f32 v132, v132, 0x3c800000, v154
	v_mul_f32_e32 v133, 0x4b800000, v132
	v_cmp_gt_f32_e32 vcc, s1, v132
	s_nop 1
	v_cndmask_b32_e32 v132, v132, v133, vcc
	v_rsq_f32_e32 v132, v132
	s_nop 0
	v_mul_f32_e32 v133, 0x45800000, v132
	v_cndmask_b32_e32 v132, v132, v133, vcc
	v_pk_mul_f32 v[124:125], v[132:133], v[124:125] op_sel_hi:[0,1]
	v_pk_mul_f32 v[126:127], v[132:133], v[126:127] op_sel_hi:[0,1]
	v_pk_mul_f32 v[134:135], v[132:133], v[128:129] op_sel_hi:[0,1]
	v_pk_mul_f32 v[132:133], v[132:133], v[130:131] op_sel_hi:[0,1]
	v_pk_mul_f32 v[130:131], v[76:77], v[124:125]
	v_pk_mul_f32 v[128:129], v[78:79], v[126:127]
	v_pk_mul_f32 v[126:127], v[72:73], v[134:135]
	v_pk_mul_f32 v[124:125], v[74:75], v[132:133]
	s_and_saveexec_b64 s[8:9], s[50:51]
	s_cbranch_execz .LBB0_356
	v_and_b32_e32 v133, 64, v104
	v_xor_b32_e32 v132, 4, v104
	v_add_u32_e32 v133, 64, v133
	v_cmp_lt_i32_e32 vcc, v132, v133
	s_nop 1
	v_cndmask_b32_e32 v104, v104, v132, vcc
	v_lshlrev_b32_e32 v104, 2, v104
	ds_bpermute_b32 v132, v104, v130
	ds_bpermute_b32 v133, v104, v131
	s_waitcnt lgkmcnt(0)
	v_pk_mul_f32 v[98:99], v[98:99], v[132:133]
	ds_bpermute_b32 v132, v104, v128
	ds_bpermute_b32 v133, v104, v129
	v_cndmask_b32_e64 v99, v99, -v99, s[38:39]
	v_cndmask_b32_e64 v98, v98, -v98, s[38:39]
	v_pk_fma_f32 v[130:131], v[96:97], v[130:131], v[98:99]
	s_waitcnt lgkmcnt(0)
	v_pk_mul_f32 v[94:95], v[94:95], v[132:133]
	ds_bpermute_b32 v132, v104, v126
	ds_bpermute_b32 v133, v104, v127
	v_cndmask_b32_e64 v95, v95, -v95, s[38:39]
	v_cndmask_b32_e64 v94, v94, -v94, s[38:39]
	v_pk_fma_f32 v[128:129], v[92:93], v[128:129], v[94:95]
	s_waitcnt lgkmcnt(0)
	v_pk_mul_f32 v[90:91], v[90:91], v[132:133]
	ds_bpermute_b32 v132, v104, v124
	ds_bpermute_b32 v133, v104, v125
	v_cndmask_b32_e64 v91, v91, -v91, s[38:39]
	v_cndmask_b32_e64 v90, v90, -v90, s[38:39]
	v_pk_fma_f32 v[126:127], v[88:89], v[126:127], v[90:91]
	s_waitcnt lgkmcnt(0)
	v_pk_mul_f32 v[86:87], v[86:87], v[132:133]
	s_nop 0
	v_cndmask_b32_e64 v87, v87, -v87, s[38:39]
	v_cndmask_b32_e64 v86, v86, -v86, s[38:39]
	v_pk_fma_f32 v[124:125], v[84:85], v[124:125], v[86:87]

.LBB0_1705:
	s_add_i32 s90, s14, 2
	v_add_u32_e32 v0, s2, v231
	ds_read_b64_tr_b16 v[194:195], v0 offset:24576
	ds_read_b64_tr_b16 v[196:197], v0 offset:25088
	s_waitcnt lgkmcnt(9)
	v_mfma_f32_32x32x16_bf16 v[96:111], v[190:193], v[142:145], 0
	v_add_f32_e32 v2, v64, v65
	v_add_f32_e32 v2, v66, v2
	v_add_f32_e32 v2, v67, v2
	v_add_f32_e32 v2, v68, v2
	v_add_f32_e32 v2, v69, v2
	v_cvt_pk_bf16_f32 v158, v64, v65
	v_cvt_pk_bf16_f32 v159, v66, v67
	ds_read_b64_tr_b16 v[10:11], v0 offset:28672
	ds_read_b64_tr_b16 v[12:13], v0 offset:29184
	s_waitcnt lgkmcnt(10)
	v_mfma_f32_32x32x16_bf16 v[114:129], v[182:185], v[142:145], 0
	v_add_f32_e32 v2, v70, v2
	v_add_f32_e32 v2, v71, v2
	v_add_f32_e32 v2, v72, v2
	v_add_f32_e32 v6, v73, v2
	v_cvt_pk_bf16_f32 v160, v68, v69
	v_cvt_pk_bf16_f32 v161, v70, v71
	ds_read_b64_tr_b16 v[2:3], v0 offset:25600
	ds_read_b64_tr_b16 v[4:5], v0 offset:26112
	s_waitcnt lgkmcnt(11)
	v_mfma_f32_32x32x16_bf16 v[96:111], v[186:189], v[138:141], v[96:111]
	v_add_f32_e32 v6, v74, v6
	v_add_f32_e32 v6, v75, v6
	v_add_f32_e32 v6, v76, v6
	v_add_f32_e32 v14, v77, v6
	v_cvt_pk_bf16_f32 v154, v72, v73
	v_cvt_pk_bf16_f32 v155, v74, v75
	ds_read_b64_tr_b16 v[6:7], v0 offset:29696
	ds_read_b64_tr_b16 v[8:9], v0 offset:30208
	s_waitcnt lgkmcnt(12)
	v_mfma_f32_32x32x16_bf16 v[114:129], v[178:181], v[138:141], v[114:129]
	v_add_f32_e32 v14, v78, v14
	v_add_f32_e32 v14, v79, v14
	v_add_f32_e32 v14, v80, v14
	v_add_f32_e32 v14, v81, v14
	v_cvt_pk_bf16_f32 v156, v76, v77
	v_cvt_pk_bf16_f32 v157, v78, v79
	ds_read_b64_tr_b16 v[178:179], v0 offset:26624
	ds_read_b64_tr_b16 v[180:181], v0 offset:27136
	s_waitcnt lgkmcnt(13)
	v_mfma_f32_32x32x16_bf16 v[96:111], v[174:177], v[134:137], v[96:111]
	v_add_f32_e32 v14, v82, v14
	v_add_f32_e32 v14, v83, v14
	v_add_f32_e32 v14, v84, v14
	v_add_f32_e32 v14, v85, v14
	v_cvt_pk_bf16_f32 v150, v80, v81
	v_cvt_pk_bf16_f32 v151, v82, v83
	ds_read_b64_tr_b16 v[174:175], v0 offset:30720
	ds_read_b64_tr_b16 v[176:177], v0 offset:31232
	s_waitcnt lgkmcnt(14)
	v_mfma_f32_32x32x16_bf16 v[114:129], v[170:173], v[134:137], v[114:129]
	v_add_f32_e32 v14, v86, v14
	v_add_f32_e32 v14, v87, v14
	v_add_f32_e32 v14, v88, v14
	v_add_f32_e32 v14, v89, v14
	v_cvt_pk_bf16_f32 v152, v84, v85
	v_cvt_pk_bf16_f32 v153, v86, v87
	ds_read_b64_tr_b16 v[170:171], v0 offset:27648
	ds_read_b64_tr_b16 v[172:173], v0 offset:28160
	s_waitcnt lgkmcnt(14)
	v_mfma_f32_32x32x16_bf16 v[96:111], v[166:169], v[130:133], v[96:111]
	v_add_f32_e32 v14, v90, v14
	v_add_f32_e32 v14, v91, v14
	v_add_f32_e32 v14, v92, v14
	v_add_f32_e32 v14, v93, v14
	v_cvt_pk_bf16_f32 v146, v88, v89
	v_cvt_pk_bf16_f32 v147, v90, v91
	ds_read_b64_tr_b16 v[166:167], v0 offset:31744
	ds_read_b64_tr_b16 v[168:169], v0 offset:32256
	v_mfma_f32_32x32x16_bf16 v[114:129], v[162:165], v[130:133], v[114:129]
	v_add_f32_e32 v0, v94, v14
	v_add_f32_e32 v0, v95, v0
	v_add_f32_e32 v0, 0, v0
	v_cvt_pk_bf16_f32 v148, v92, v93
	v_cvt_pk_bf16_f32 v149, v94, v95
	s_add_i32 s7, s14, 5
	s_cmp_lt_i32 s7, s0
	s_cselect_b32 s2, s7, s12
	s_cmp_gt_i32 s7, s6
	s_cselect_b32 s9, s95, 0
	s_cselect_b32 s8, s13, 0
	s_lshl_b64 s[10:11], s[2:3], 18
	v_lshl_add_u64 v[14:15], v[214:215], 0, s[10:11]
	s_add_i32 s2, s15, s97
	v_lshl_add_u64 v[14:15], s[8:9], 1, v[14:15]
	s_mov_b32 s7, m0
	s_mov_b32 m0, s2
	s_nop 0
	global_load_lds_dwordx4 v[14:15], off
	s_mov_b32 m0, s7
	s_add_i32 s2, s14, 3
	s_cmp_ge_i32 s2, s0
	s_cselect_b64 s[34:35], -1, 0
	s_cmp_lt_i32 s2, s0
	s_cselect_b32 s2, s2, s12
	s_cmp_ge_i32 s90, s6
	s_cselect_b64 s[36:37], -1, 0
	s_cmp_lt_i32 s90, s6
	s_cselect_b32 s9, 0, s95
	s_cselect_b32 s8, 0, s13
	s_lshl_b64 s[10:11], s[2:3], 18
	v_lshl_add_u64 v[14:15], v[216:217], 0, s[10:11]
	s_add_i32 s2, s89, s92
	v_lshl_add_u64 v[14:15], s[8:9], 1, v[14:15]
	s_mov_b32 s7, m0
	s_mov_b32 m0, s2
	s_nop 0
	global_load_lds_dwordx4 v[14:15], off
	s_mov_b32 m0, s7
	s_cmp_gt_i32 s90, s6
	s_cselect_b64 s[8:9], -1, 0
	v_pk_add_f32 v[112:113], v[96:97], v[218:219] op_sel_hi:[1,0] neg_lo:[0,1] neg_hi:[0,1]
	v_pk_add_f32 v[96:97], v[114:115], v[218:219] op_sel_hi:[1,0] neg_lo:[0,1] neg_hi:[0,1]
	v_pk_add_f32 v[114:115], v[98:99], v[218:219] op_sel_hi:[1,0] neg_lo:[0,1] neg_hi:[0,1]
	v_pk_add_f32 v[98:99], v[116:117], v[218:219] op_sel_hi:[1,0] neg_lo:[0,1] neg_hi:[0,1]
	v_pk_add_f32 v[116:117], v[100:101], v[218:219] op_sel_hi:[1,0] neg_lo:[0,1] neg_hi:[0,1]
	v_pk_add_f32 v[100:101], v[118:119], v[218:219] op_sel_hi:[1,0] neg_lo:[0,1] neg_hi:[0,1]
	v_pk_add_f32 v[118:119], v[102:103], v[218:219] op_sel_hi:[1,0] neg_lo:[0,1] neg_hi:[0,1]
	v_pk_add_f32 v[102:103], v[120:121], v[218:219] op_sel_hi:[1,0] neg_lo:[0,1] neg_hi:[0,1]
	v_pk_add_f32 v[120:121], v[104:105], v[218:219] op_sel_hi:[1,0] neg_lo:[0,1] neg_hi:[0,1]
	v_pk_add_f32 v[104:105], v[122:123], v[218:219] op_sel_hi:[1,0] neg_lo:[0,1] neg_hi:[0,1]
	v_pk_add_f32 v[122:123], v[106:107], v[218:219] op_sel_hi:[1,0] neg_lo:[0,1] neg_hi:[0,1]
	v_pk_add_f32 v[106:107], v[124:125], v[218:219] op_sel_hi:[1,0] neg_lo:[0,1] neg_hi:[0,1]
	v_pk_add_f32 v[124:125], v[108:109], v[218:219] op_sel_hi:[1,0] neg_lo:[0,1] neg_hi:[0,1]
	v_pk_add_f32 v[108:109], v[126:127], v[218:219] op_sel_hi:[1,0] neg_lo:[0,1] neg_hi:[0,1]
	v_pk_add_f32 v[126:127], v[110:111], v[218:219] op_sel_hi:[1,0] neg_lo:[0,1] neg_hi:[0,1]
	v_pk_add_f32 v[110:111], v[128:129], v[218:219] op_sel_hi:[1,0] neg_lo:[0,1] neg_hi:[0,1]
	s_mov_b64 s[10:11], -1
	s_and_b64 vcc, exec, s[8:9]
	s_cbranch_vccnz .LBB0_1742
	s_add_i32 s2, s96, s14
	s_add_i32 s2, s2, 2
	s_cmp_lt_u32 s2, s93
	s_cselect_b64 s[10:11], -1, 0
	s_cmp_gt_u32 s2, s1
	s_cselect_b64 vcc, -1, 0
	s_or_b64 s[10:11], s[10:11], vcc
	s_and_b64 vcc, exec, s[10:11]
	s_cbranch_vccnz .LBB0_1740
	ds_read_b32 v14, v207 offset:128
	v_mov_b32_e32 v65, 0xc6ea6000
	v_mov_b32_e32 v64, 0xc6ea6000
	ds_read_b32 v235, v207
	ds_read_b32 v15, v207 offset:132
	ds_read_b32 v236, v207 offset:4
	ds_read_b32 v17, v207 offset:136
	v_mov_b32_e32 v67, 0xc6ea6000
	v_mov_b32_e32 v66, 0xc6ea6000
	ds_read_b32 v237, v207 offset:8
	ds_read_b32 v18, v207 offset:140
	ds_read_b32 v238, v207 offset:12
	s_waitcnt lgkmcnt(0)
	v_add_f32_e32 v251, v112, v235
	v_cndmask_b32_e64 v64, v64, v251, s[40:41]
	v_add_f32_e32 v251, v113, v236
	v_cndmask_b32_e64 v65, v65, v251, s[44:45]
	v_add_f32_e32 v251, v114, v237
	v_cndmask_b32_e64 v66, v66, v251, s[48:49]
	v_add_f32_e32 v251, v115, v238
	v_cndmask_b32_e64 v67, v67, v251, s[52:53]
	ds_read_b32 v19, v207 offset:160
	v_mov_b32_e32 v69, 0xc6ea6000
	v_mov_b32_e32 v68, 0xc6ea6000
	ds_read_b32 v239, v207 offset:32
	ds_read_b32 v20, v207 offset:164
	ds_read_b32 v240, v207 offset:36
	ds_read_b32 v21, v207 offset:168
	v_mov_b32_e32 v71, 0xc6ea6000
	v_mov_b32_e32 v70, 0xc6ea6000
	ds_read_b32 v241, v207 offset:40
	ds_read_b32 v22, v207 offset:172
	ds_read_b32 v242, v207 offset:44
	s_waitcnt lgkmcnt(0)
	v_add_f32_e32 v251, v116, v239
	v_cndmask_b32_e64 v68, v68, v251, s[56:57]
	v_add_f32_e32 v251, v117, v240
	v_cndmask_b32_e64 v69, v69, v251, s[60:61]
	v_add_f32_e32 v251, v118, v241
	v_cndmask_b32_e64 v70, v70, v251, s[64:65]
	v_add_f32_e32 v251, v119, v242
	v_cndmask_b32_e64 v71, v71, v251, s[68:69]
	ds_read_b32 v23, v207 offset:192
	v_mov_b32_e32 v73, 0xc6ea6000
	v_mov_b32_e32 v72, 0xc6ea6000
	ds_read_b32 v243, v207 offset:64
	ds_read_b32 v24, v207 offset:196
	ds_read_b32 v244, v207 offset:68
	ds_read_b32 v25, v207 offset:200
	v_mov_b32_e32 v75, 0xc6ea6000
	v_mov_b32_e32 v74, 0xc6ea6000
	ds_read_b32 v245, v207 offset:72
	ds_read_b32 v26, v207 offset:204
	ds_read_b32 v246, v207 offset:76
	s_waitcnt lgkmcnt(0)
	v_add_f32_e32 v251, v120, v243
	v_cndmask_b32_e64 v72, v72, v251, s[16:17]
	v_add_f32_e32 v251, v121, v244
	v_cndmask_b32_e64 v73, v73, v251, s[18:19]
	v_add_f32_e32 v251, v122, v245
	v_cndmask_b32_e64 v74, v74, v251, s[20:21]
	v_add_f32_e32 v251, v123, v246
	v_cndmask_b32_e64 v75, v75, v251, s[22:23]
	ds_read_b32 v27, v207 offset:224
	v_mov_b32_e32 v77, 0xc6ea6000
	v_mov_b32_e32 v76, 0xc6ea6000
	ds_read_b32 v247, v207 offset:96
	ds_read_b32 v28, v207 offset:228
	ds_read_b32 v248, v207 offset:100
	ds_read_b32 v29, v207 offset:232
	v_mov_b32_e32 v79, 0xc6ea6000
	v_mov_b32_e32 v78, 0xc6ea6000
	ds_read_b32 v249, v207 offset:104
	ds_read_b32 v30, v207 offset:236
	ds_read_b32 v250, v207 offset:108
	s_waitcnt lgkmcnt(0)
	v_add_f32_e32 v251, v124, v247
	v_cndmask_b32_e64 v76, v76, v251, s[24:25]
	v_add_f32_e32 v251, v125, v248
	v_cndmask_b32_e64 v77, v77, v251, s[26:27]
	v_add_f32_e32 v251, v126, v249
	v_cndmask_b32_e64 v78, v78, v251, s[28:29]
	v_add_f32_e32 v251, v127, v250
	v_cndmask_b32_e64 v79, v79, v251, s[30:31]
	s_waitcnt lgkmcnt(14)
	v_add_f32_e32 v14, v96, v14
	v_cndmask_b32_e64 v80, v16, v14, s[42:43]
	v_add_f32_e32 v14, v97, v15
	v_cndmask_b32_e64 v81, v16, v14, s[46:47]
	s_waitcnt lgkmcnt(13)
	v_add_f32_e32 v14, v98, v17
	v_cndmask_b32_e64 v82, v16, v14, s[50:51]
	s_waitcnt lgkmcnt(12)
	v_add_f32_e32 v14, v99, v18
	v_cndmask_b32_e64 v83, v16, v14, s[54:55]
	s_waitcnt lgkmcnt(11)
	v_add_f32_e32 v14, v100, v19
	v_cndmask_b32_e64 v84, v16, v14, s[58:59]
	s_waitcnt lgkmcnt(10)
	v_add_f32_e32 v14, v101, v20
	v_cndmask_b32_e64 v85, v16, v14, s[62:63]
	s_waitcnt lgkmcnt(9)
	v_add_f32_e32 v14, v102, v21
	v_cndmask_b32_e64 v86, v16, v14, s[66:67]
	s_waitcnt lgkmcnt(8)
	v_add_f32_e32 v14, v103, v22
	v_cndmask_b32_e64 v87, v16, v14, s[70:71]
	s_waitcnt lgkmcnt(7)
	v_add_f32_e32 v14, v104, v23
	v_cndmask_b32_e64 v88, v16, v14, s[72:73]
	s_waitcnt lgkmcnt(6)
	v_add_f32_e32 v14, v105, v24
	v_cndmask_b32_e64 v89, v16, v14, s[74:75]
	s_waitcnt lgkmcnt(5)
	v_add_f32_e32 v14, v106, v25
	v_cndmask_b32_e64 v90, v16, v14, s[76:77]
	s_waitcnt lgkmcnt(4)
	v_add_f32_e32 v14, v107, v26
	v_cndmask_b32_e64 v91, v16, v14, s[78:79]
	s_waitcnt lgkmcnt(3)
	v_add_f32_e32 v14, v108, v27
	v_cndmask_b32_e64 v92, v16, v14, s[80:81]
	s_waitcnt lgkmcnt(2)
	v_add_f32_e32 v14, v109, v28
	v_cndmask_b32_e64 v93, v16, v14, s[82:83]
	s_waitcnt lgkmcnt(1)
	v_add_f32_e32 v14, v110, v29
	v_cndmask_b32_e64 v94, v16, v14, s[84:85]
	s_waitcnt lgkmcnt(0)
	v_add_f32_e32 v14, v111, v30
	v_cndmask_b32_e64 v95, v16, v14, s[86:87]
	s_branch .LBB0_1741

.LBB0_1753:
	s_add_i32 s2, s96, s14
	s_add_i32 s2, s2, 3
	s_cmp_lt_u32 s2, s93
	s_cselect_b64 s[8:9], -1, 0
	s_cmp_gt_u32 s2, s1
	s_cselect_b64 s[10:11], -1, 0
	s_or_b64 s[8:9], s[8:9], s[10:11]
	s_and_b64 vcc, exec, s[8:9]
	s_cbranch_vccnz .LBB0_1788
	ds_read_b32 v17, v207 offset:252
	v_mov_b32_e32 v65, 0xc6ea6000
	v_mov_b32_e32 v64, 0xc6ea6000
	ds_read_b32 v235, v207 offset:124
	ds_read_b32 v18, v207 offset:256
	ds_read_b32 v236, v207 offset:128
	ds_read_b32 v19, v207 offset:260
	v_mov_b32_e32 v67, 0xc6ea6000
	v_mov_b32_e32 v66, 0xc6ea6000
	ds_read_b32 v237, v207 offset:132
	ds_read_b32 v20, v207 offset:264
	ds_read_b32 v238, v207 offset:136
	s_waitcnt lgkmcnt(0)
	v_add_f32_e32 v251, v112, v235
	v_cndmask_b32_e64 v64, v64, v251, s[40:41]
	v_add_f32_e32 v251, v113, v236
	v_cndmask_b32_e64 v65, v65, v251, s[44:45]
	v_add_f32_e32 v251, v114, v237
	v_cndmask_b32_e64 v66, v66, v251, s[48:49]
	v_add_f32_e32 v251, v115, v238
	v_cndmask_b32_e64 v67, v67, v251, s[52:53]
	ds_read_b32 v21, v207 offset:284
	v_mov_b32_e32 v69, 0xc6ea6000
	v_mov_b32_e32 v68, 0xc6ea6000
	ds_read_b32 v239, v207 offset:156
	ds_read_b32 v22, v207 offset:288
	ds_read_b32 v240, v207 offset:160
	ds_read_b32 v23, v207 offset:292
	v_mov_b32_e32 v71, 0xc6ea6000
	v_mov_b32_e32 v70, 0xc6ea6000
	ds_read_b32 v241, v207 offset:164
	ds_read_b32 v24, v207 offset:296
	ds_read_b32 v242, v207 offset:168
	s_waitcnt lgkmcnt(0)
	v_add_f32_e32 v251, v116, v239
	v_cndmask_b32_e64 v68, v68, v251, s[56:57]
	v_add_f32_e32 v251, v117, v240
	v_cndmask_b32_e64 v69, v69, v251, s[60:61]
	v_add_f32_e32 v251, v118, v241
	v_cndmask_b32_e64 v70, v70, v251, s[64:65]
	v_add_f32_e32 v251, v119, v242
	v_cndmask_b32_e64 v71, v71, v251, s[68:69]
	ds_read_b32 v25, v207 offset:316
	v_mov_b32_e32 v73, 0xc6ea6000
	v_mov_b32_e32 v72, 0xc6ea6000
	ds_read_b32 v243, v207 offset:188
	ds_read_b32 v26, v207 offset:320
	ds_read_b32 v244, v207 offset:192
	ds_read_b32 v27, v207 offset:324
	v_mov_b32_e32 v75, 0xc6ea6000
	v_mov_b32_e32 v74, 0xc6ea6000
	ds_read_b32 v245, v207 offset:196
	ds_read_b32 v28, v207 offset:328
	ds_read_b32 v246, v207 offset:200
	s_waitcnt lgkmcnt(0)
	v_add_f32_e32 v251, v120, v243
	v_cndmask_b32_e64 v72, v72, v251, s[16:17]
	v_add_f32_e32 v251, v121, v244
	v_cndmask_b32_e64 v73, v73, v251, s[18:19]
	v_add_f32_e32 v251, v122, v245
	v_cndmask_b32_e64 v74, v74, v251, s[20:21]
	v_add_f32_e32 v251, v123, v246
	v_cndmask_b32_e64 v75, v75, v251, s[22:23]
	ds_read_b32 v29, v207 offset:348
	v_mov_b32_e32 v77, 0xc6ea6000
	v_mov_b32_e32 v76, 0xc6ea6000
	ds_read_b32 v247, v207 offset:220
	ds_read_b32 v30, v207 offset:352
	ds_read_b32 v248, v207 offset:224
	ds_read_b32 v31, v207 offset:356
	v_mov_b32_e32 v79, 0xc6ea6000
	v_mov_b32_e32 v78, 0xc6ea6000
	ds_read_b32 v249, v207 offset:228
	ds_read_b32 v95, v207 offset:360
	ds_read_b32 v250, v207 offset:232
	s_waitcnt lgkmcnt(0)
	v_add_f32_e32 v251, v124, v247
	v_cndmask_b32_e64 v76, v76, v251, s[24:25]
	v_add_f32_e32 v251, v125, v248
	v_cndmask_b32_e64 v77, v77, v251, s[26:27]
	v_add_f32_e32 v251, v126, v249
	v_cndmask_b32_e64 v78, v78, v251, s[28:29]
	v_add_f32_e32 v251, v127, v250
	v_cndmask_b32_e64 v79, v79, v251, s[30:31]
	s_waitcnt lgkmcnt(14)
	v_add_f32_e32 v17, v96, v17
	v_cndmask_b32_e64 v80, v16, v17, s[42:43]
	v_add_f32_e32 v17, v97, v18
	v_cndmask_b32_e64 v81, v16, v17, s[46:47]
	s_waitcnt lgkmcnt(13)
	v_add_f32_e32 v17, v98, v19
	v_cndmask_b32_e64 v82, v16, v17, s[50:51]
	s_waitcnt lgkmcnt(12)
	v_add_f32_e32 v17, v99, v20
	v_cndmask_b32_e64 v83, v16, v17, s[54:55]
	s_waitcnt lgkmcnt(11)
	v_add_f32_e32 v17, v100, v21
	v_cndmask_b32_e64 v84, v16, v17, s[58:59]
	s_waitcnt lgkmcnt(10)
	v_add_f32_e32 v17, v101, v22
	v_cndmask_b32_e64 v85, v16, v17, s[62:63]
	s_waitcnt lgkmcnt(9)
	v_add_f32_e32 v17, v102, v23
	v_cndmask_b32_e64 v86, v16, v17, s[66:67]
	s_waitcnt lgkmcnt(8)
	v_add_f32_e32 v17, v103, v24
	v_cndmask_b32_e64 v87, v16, v17, s[70:71]
	s_waitcnt lgkmcnt(7)
	v_add_f32_e32 v17, v104, v25
	v_cndmask_b32_e64 v88, v16, v17, s[72:73]
	s_waitcnt lgkmcnt(6)
	v_add_f32_e32 v17, v105, v26
	v_cndmask_b32_e64 v89, v16, v17, s[74:75]
	s_waitcnt lgkmcnt(5)
	v_add_f32_e32 v17, v106, v27
	v_cndmask_b32_e64 v90, v16, v17, s[76:77]
	s_waitcnt lgkmcnt(4)
	v_add_f32_e32 v17, v107, v28
	v_cndmask_b32_e64 v91, v16, v17, s[78:79]
	s_waitcnt lgkmcnt(3)
	v_add_f32_e32 v17, v108, v29
	v_cndmask_b32_e64 v92, v16, v17, s[80:81]
	s_waitcnt lgkmcnt(2)
	v_add_f32_e32 v17, v109, v30
	v_cndmask_b32_e64 v93, v16, v17, s[82:83]
	s_waitcnt lgkmcnt(1)
	v_add_f32_e32 v17, v110, v31
	v_cndmask_b32_e64 v94, v16, v17, s[84:85]
	s_waitcnt lgkmcnt(0)
	v_add_f32_e32 v17, v111, v95
	v_cndmask_b32_e64 v95, v16, v17, s[86:87]
	s_branch .LBB0_1789
